# attention loop: second key-half softmax VALU interleaved under the first-half PV MFMAs
# speedup vs baseline: 1.0487x; 1.0029x over previous
; #define MFMA16(a, b, c) __builtin_amdgcn_mfma_f32_16x16x32_bf16((a), (b), (c), 0, 0, 0)
; DI unsigned pack2(float a, float b) { f2_t v = {a, b}; return __builtin_bit_cast(unsigned, __builtin_convertvector(v, bf2_t)); }
; DI void diff_attn_item(const Params& p, int layer, int qb, int bh, char* lds) {
;     ...
;       bf16x8 pf[2][2];
; #pragma unroll
;       for (int qt = 0; qt < 2; ++qt) {
;         float psum = 0.f;
; #pragma unroll
;         for (int ksub = 0; ksub < 4; ++ksub)
; #pragma unroll
;           for (int r = 0; r < 4; ++r) { const float e = __builtin_amdgcn_exp2f(S[ksub][qt][r]); S[ksub][qt][r] = e; psum += e; }
;         l[qt] += psum;
; #pragma unroll
;         for (int kk = 0; kk < 2; ++kk) {
;           union { unsigned u[4]; bf16x8 v; } pk;
;           pk.u[0] = pack2(S[2 * kk][qt][0], S[2 * kk][qt][1]);
;           pk.u[1] = pack2(S[2 * kk][qt][2], S[2 * kk][qt][3]);
;           pk.u[2] = pack2(S[2 * kk + 1][qt][0], S[2 * kk + 1][qt][1]);
;           pk.u[3] = pack2(S[2 * kk + 1][qt][2], S[2 * kk + 1][qt][3]);
;           pf[kk][qt] = pk.v;
;         }
;       }
;       __builtin_amdgcn_sched_barrier(0);
; #pragma unroll
;       for (int d = 0; d < 8; ++d) { const int row = d * 16 + c16; vfb[d] = *(const bf16x8*)(Vb + row * 128 + (swz(row, 4 + quad) << 4)); }
; #pragma unroll
;       for (int d = 0; d < 8; ++d)
; #pragma unroll
;         for (int qt = 0; qt < 2; ++qt) O[d][qt] = MFMA16(vfa[d], pf[0][qt], O[d][qt]);
;       __builtin_amdgcn_sched_barrier(0);
; #pragma unroll
;       for (int d = 0; d < 8; ++d)
; #pragma unroll
;         for (int qt = 0; qt < 2; ++qt) O[d][qt] = MFMA16(vfb[d], pf[1][qt], O[d][qt]);
.LBB0_1268:
	v_exp_f32_e32 v140, v140
	v_exp_f32_e32 v204, v141
	v_exp_f32_e32 v141, v128
	v_exp_f32_e32 v205, v129
	v_exp_f32_e32 v142, v142
	v_exp_f32_e32 v206, v143
	v_exp_f32_e32 v143, v130
	v_exp_f32_e32 v207, v131
	v_exp_f32_e32 v208, v136
	v_exp_f32_e32 v209, v120
	v_exp_f32_e32 v211, v121
	v_pk_add_f32 v[120:121], v[140:141], 0 op_sel_hi:[1,0]
	v_exp_f32_e32 v210, v137
	v_pk_add_f32 v[120:121], v[120:121], v[204:205]
	v_exp_f32_e32 v212, v138
	v_exp_f32_e32 v213, v122
	v_pk_add_f32 v[120:121], v[142:143], v[120:121]
	v_exp_f32_e32 v214, v139
	v_pk_add_f32 v[120:121], v[206:207], v[120:121]
	v_exp_f32_e32 v215, v123
	v_pk_add_f32 v[120:121], v[208:209], v[120:121]
	v_cvt_pk_bf16_f32 v232, v140, v204
	v_pk_add_f32 v[120:121], v[210:211], v[120:121]
	v_cvt_pk_bf16_f32 v233, v142, v206
	v_pk_add_f32 v[120:121], v[212:213], v[120:121]
	v_cvt_pk_bf16_f32 v234, v208, v210
	v_pk_add_f32 v[120:121], v[214:215], v[120:121]
	v_cvt_pk_bf16_f32 v235, v212, v214
	v_cvt_pk_bf16_f32 v236, v141, v205
	v_cvt_pk_bf16_f32 v237, v143, v207
	v_cvt_pk_bf16_f32 v238, v209, v211
	v_cvt_pk_bf16_f32 v239, v213, v215
	v_add3_u32 v240, s8, v201, v198
	s_waitcnt lgkmcnt(0)
	v_mfma_f32_16x16x32_bf16 v[64:67], v[108:111], v[232:235], v[64:67]
	v_exp_f32_e32 v216, v132
	v_exp_f32_e32 v217, v116
	v_mfma_f32_16x16x32_bf16 v[32:35], v[108:111], v[236:239], v[32:35]
	v_exp_f32_e32 v218, v133
	v_exp_f32_e32 v219, v117
	v_mfma_f32_16x16x32_bf16 v[68:71], v[112:115], v[232:235], v[68:71]
	v_exp_f32_e32 v220, v134
	v_exp_f32_e32 v221, v118
	v_mfma_f32_16x16x32_bf16 v[28:31], v[112:115], v[236:239], v[28:31]
	v_exp_f32_e32 v222, v135
	v_exp_f32_e32 v223, v119
	v_mfma_f32_16x16x32_bf16 v[72:75], v[104:107], v[232:235], v[72:75]
	v_exp_f32_e32 v144, v144
	v_exp_f32_e32 v224, v145
	v_mfma_f32_16x16x32_bf16 v[24:27], v[104:107], v[236:239], v[24:27]
	v_exp_f32_e32 v145, v124
	v_exp_f32_e32 v225, v125
	v_mfma_f32_16x16x32_bf16 v[76:79], v[96:99], v[232:235], v[76:79]
	v_exp_f32_e32 v146, v146
	v_exp_f32_e32 v226, v147
	v_mfma_f32_16x16x32_bf16 v[20:23], v[96:99], v[236:239], v[20:23]
	v_exp_f32_e32 v147, v126
	v_exp_f32_e32 v227, v127
	v_mfma_f32_16x16x32_bf16 v[80:83], v[100:103], v[232:235], v[80:83]
	v_pk_add_f32 v[120:121], v[216:217], v[120:121]
	v_pk_add_f32 v[120:121], v[218:219], v[120:121]
	v_mfma_f32_16x16x32_bf16 v[16:19], v[100:103], v[236:239], v[16:19]
	v_pk_add_f32 v[120:121], v[220:221], v[120:121]
	v_pk_add_f32 v[120:121], v[222:223], v[120:121]
	v_mfma_f32_16x16x32_bf16 v[60:63], v[92:95], v[232:235], v[60:63]
	v_pk_add_f32 v[120:121], v[144:145], v[120:121]
	v_pk_add_f32 v[120:121], v[224:225], v[120:121]
	v_mfma_f32_16x16x32_bf16 v[12:15], v[92:95], v[236:239], v[12:15]
	v_pk_add_f32 v[120:121], v[146:147], v[120:121]
	v_pk_add_f32 v[120:121], v[226:227], v[120:121]
	v_mfma_f32_16x16x32_bf16 v[56:59], v[88:91], v[232:235], v[56:59]
	v_pk_add_f32 v[156:157], v[156:157], v[120:121]
	v_cvt_pk_bf16_f32 v136, v216, v218
	v_mfma_f32_16x16x32_bf16 v[8:11], v[88:91], v[236:239], v[8:11]
	v_cvt_pk_bf16_f32 v137, v220, v222
	v_cvt_pk_bf16_f32 v138, v144, v224
	ds_read_b128 v[88:91], v240 offset:16384
	ds_read_b128 v[92:95], v240 offset:18432
	ds_read_b128 v[96:99], v240 offset:20480
	ds_read_b128 v[100:103], v240 offset:22528
	ds_read_b128 v[104:107], v240 offset:24576
	ds_read_b128 v[108:111], v240 offset:26624
	ds_read_b128 v[112:115], v240 offset:28672
	ds_read_b128 v[124:127], v240 offset:30720
	v_mfma_f32_16x16x32_bf16 v[52:55], v[84:87], v[232:235], v[52:55]
	v_cvt_pk_bf16_f32 v139, v146, v226
	v_cvt_pk_bf16_f32 v120, v217, v219
	v_mfma_f32_16x16x32_bf16 v[4:7], v[84:87], v[236:239], v[4:7]
	v_cvt_pk_bf16_f32 v121, v221, v223
	v_cvt_pk_bf16_f32 v122, v145, v225
	v_cvt_pk_bf16_f32 v123, v147, v227
	s_nop 0
	s_waitcnt lgkmcnt(0)
	v_mfma_f32_16x16x32_bf16 v[64:67], v[88:91], v[136:139], v[64:67]
	v_mfma_f32_16x16x32_bf16 v[32:35], v[88:91], v[120:123], v[32:35]
	v_mfma_f32_16x16x32_bf16 v[68:71], v[92:95], v[136:139], v[68:71]
	v_mfma_f32_16x16x32_bf16 v[28:31], v[92:95], v[120:123], v[28:31]
	v_mfma_f32_16x16x32_bf16 v[72:75], v[96:99], v[136:139], v[72:75]
	v_mfma_f32_16x16x32_bf16 v[24:27], v[96:99], v[120:123], v[24:27]
	v_mfma_f32_16x16x32_bf16 v[76:79], v[100:103], v[136:139], v[76:79]
	v_mfma_f32_16x16x32_bf16 v[20:23], v[100:103], v[120:123], v[20:23]
	v_mfma_f32_16x16x32_bf16 v[80:83], v[104:107], v[136:139], v[80:83]
	v_mfma_f32_16x16x32_bf16 v[16:19], v[104:107], v[120:123], v[16:19]
	v_mfma_f32_16x16x32_bf16 v[60:63], v[108:111], v[136:139], v[60:63]
	v_mfma_f32_16x16x32_bf16 v[12:15], v[108:111], v[120:123], v[12:15]
	v_mfma_f32_16x16x32_bf16 v[56:59], v[112:115], v[136:139], v[56:59]
	v_mfma_f32_16x16x32_bf16 v[8:11], v[112:115], v[120:123], v[8:11]
	v_mfma_f32_16x16x32_bf16 v[52:55], v[124:127], v[136:139], v[52:55]
	v_mfma_f32_16x16x32_bf16 v[4:7], v[124:127], v[120:123], v[4:7]
